# single accumulator zeroing per tile (second redundant 128-register clear before the K-loop removed)
# speedup vs baseline: 1.0288x; 1.0044x over previous
.LBB0_623:
	v_mov_b32_e32 v123, 0
	s_andn2_b64 vcc, exec, s[22:23]
	v_mov_b32_e32 v122, v123
	v_mov_b32_e32 v121, v123
	v_mov_b32_e32 v120, v123
	v_mov_b32_e32 v115, v123
	v_mov_b32_e32 v114, v123
	v_mov_b32_e32 v113, v123
	v_mov_b32_e32 v112, v123
	v_mov_b32_e32 v107, v123
	v_mov_b32_e32 v106, v123
	v_mov_b32_e32 v105, v123
	v_mov_b32_e32 v104, v123
	v_mov_b32_e32 v99, v123
	v_mov_b32_e32 v98, v123
	v_mov_b32_e32 v97, v123
	v_mov_b32_e32 v96, v123
	v_mov_b32_e32 v91, v123
	v_mov_b32_e32 v90, v123
	v_mov_b32_e32 v89, v123
	v_mov_b32_e32 v88, v123
	v_mov_b32_e32 v83, v123
	v_mov_b32_e32 v82, v123
	v_mov_b32_e32 v81, v123
	v_mov_b32_e32 v80, v123
	v_mov_b32_e32 v75, v123
	v_mov_b32_e32 v74, v123
	v_mov_b32_e32 v73, v123
	v_mov_b32_e32 v72, v123
	v_mov_b32_e32 v67, v123
	v_mov_b32_e32 v66, v123
	v_mov_b32_e32 v65, v123
	v_mov_b32_e32 v64, v123
	v_mov_b32_e32 v127, v123
	v_mov_b32_e32 v126, v123
	v_mov_b32_e32 v125, v123
	v_mov_b32_e32 v124, v123
	v_mov_b32_e32 v119, v123
	v_mov_b32_e32 v118, v123
	v_mov_b32_e32 v117, v123
	v_mov_b32_e32 v116, v123
	v_mov_b32_e32 v111, v123
	v_mov_b32_e32 v110, v123
	v_mov_b32_e32 v109, v123
	v_mov_b32_e32 v108, v123
	v_mov_b32_e32 v103, v123
	v_mov_b32_e32 v102, v123
	v_mov_b32_e32 v101, v123
	v_mov_b32_e32 v100, v123
	v_mov_b32_e32 v95, v123
	v_mov_b32_e32 v94, v123
	v_mov_b32_e32 v93, v123
	v_mov_b32_e32 v92, v123
	v_mov_b32_e32 v87, v123
	v_mov_b32_e32 v86, v123
	v_mov_b32_e32 v85, v123
	v_mov_b32_e32 v84, v123
	v_mov_b32_e32 v79, v123
	v_mov_b32_e32 v78, v123
	v_mov_b32_e32 v77, v123
	v_mov_b32_e32 v76, v123
	v_mov_b32_e32 v71, v123
	v_mov_b32_e32 v70, v123
	v_mov_b32_e32 v69, v123
	v_mov_b32_e32 v68, v123
	v_mov_b32_e32 v59, v123
	v_mov_b32_e32 v58, v123
	v_mov_b32_e32 v57, v123
	v_mov_b32_e32 v56, v123
	v_mov_b32_e32 v51, v123
	v_mov_b32_e32 v50, v123
	v_mov_b32_e32 v49, v123
	v_mov_b32_e32 v48, v123
	v_mov_b32_e32 v43, v123
	v_mov_b32_e32 v42, v123
	v_mov_b32_e32 v41, v123
	v_mov_b32_e32 v40, v123
	v_mov_b32_e32 v35, v123
	v_mov_b32_e32 v34, v123
	v_mov_b32_e32 v33, v123
	v_mov_b32_e32 v32, v123
	v_mov_b32_e32 v27, v123
	v_mov_b32_e32 v26, v123
	v_mov_b32_e32 v25, v123
	v_mov_b32_e32 v24, v123
	v_mov_b32_e32 v19, v123
	v_mov_b32_e32 v18, v123
	v_mov_b32_e32 v17, v123
	v_mov_b32_e32 v16, v123
	v_mov_b32_e32 v11, v123
	v_mov_b32_e32 v10, v123
	v_mov_b32_e32 v9, v123
	v_mov_b32_e32 v8, v123
	v_mov_b32_e32 v3, v123
	v_mov_b32_e32 v2, v123
	v_mov_b32_e32 v1, v123
	v_mov_b32_e32 v0, v123
	v_mov_b32_e32 v63, v123
	v_mov_b32_e32 v62, v123
	v_mov_b32_e32 v61, v123
	v_mov_b32_e32 v60, v123
	v_mov_b32_e32 v55, v123
	v_mov_b32_e32 v54, v123
	v_mov_b32_e32 v53, v123
	v_mov_b32_e32 v52, v123
	v_mov_b32_e32 v47, v123
	v_mov_b32_e32 v46, v123
	v_mov_b32_e32 v45, v123
	v_mov_b32_e32 v44, v123
	v_mov_b32_e32 v39, v123
	v_mov_b32_e32 v38, v123
	v_mov_b32_e32 v37, v123
	v_mov_b32_e32 v36, v123
	v_mov_b32_e32 v31, v123
	v_mov_b32_e32 v30, v123
	v_mov_b32_e32 v29, v123
	v_mov_b32_e32 v28, v123
	v_mov_b32_e32 v23, v123
	v_mov_b32_e32 v22, v123
	v_mov_b32_e32 v21, v123
	v_mov_b32_e32 v20, v123
	v_mov_b32_e32 v15, v123
	v_mov_b32_e32 v14, v123
	v_mov_b32_e32 v13, v123
	v_mov_b32_e32 v12, v123
	v_mov_b32_e32 v7, v123
	v_mov_b32_e32 v6, v123
	v_mov_b32_e32 v5, v123
	v_mov_b32_e32 v4, v123
	s_cbranch_vccnz .LBB0_626
	s_add_u32 s6, s6, 0x80
	s_addc_u32 s7, s7, 0
	s_add_u32 s1, s56, 0x100
	s_addc_u32 s2, s57, 0
	s_mov_b32 s34, 0
